# v67 + code placement: MLP1_1 and MLP2_1 shifted by 4 bytes
# speedup vs baseline: 1.0062x; 1.0062x over previous
.LBB0_1609:
	s_nop 0
	s_cmp_lt_i32 s58, 17
	s_cselect_b64 s[0:1], -1, 0
	s_and_b64 s[2:3], s[0:1], s[4:5]
	s_andn2_b64 vcc, exec, s[2:3]
	s_cbranch_vccnz .LBB0_1626
	s_cmpk_gt_i32 s94, 0x4ff
	v_readfirstlane_b32 s5, v0
	s_cbranch_scc1 .LBB0_1626
	v_lshrrev_b32_e32 v1, 5, v0
	v_lshrrev_b32_e32 v3, 1, v0
	v_and_b32_e32 v1, 4, v1
	v_bfe_u32 v2, v0, 2, 2
	v_and_b32_e32 v3, 24, v3
	s_add_u32 s2, s56, 0x3500000
	s_movk_i32 s4, 0x200
	v_or3_b32 v1, v1, v2, v3
	v_bfe_u32 v3, v0, 3, 25
	s_addc_u32 s3, s57, 0
	v_or_b32_e32 v3, 64, v3
	s_movk_i32 s6, 0x60
	v_cmp_gt_u32_e32 vcc, s4, v0
	v_bfe_u32 v12, v0, 2, 4
	s_movk_i32 s4, 0x70
	s_ashr_i32 s13, s94, 31
	v_and_or_b32 v4, v3, s6, v1
	v_and_or_b32 v3, v3, s4, v12
	s_lshr_b32 s4, s13, 29
	s_add_i32 s4, s94, s4
	s_lshr_b32 s8, s5, 6
	s_and_b32 s6, s4, -8
	s_lshr_b32 s9, s5, 8
	s_lshl_b32 s12, s8, 10
	s_sub_i32 s6, s94, s6
	s_cmp_lt_i32 s6, 0
	s_movk_i32 s18, 0xa1
	s_cselect_b32 s7, s18, 0xa0
	s_mul_i32 s6, s6, s7
	s_ashr_i32 s4, s4, 3
	s_add_i32 s4, s6, s4
	s_ashr_i32 s6, s4, 31
	s_lshr_b32 s6, s6, 25
	s_add_i32 s6, s4, s6
	s_ashr_i32 s7, s6, 7
	s_and_b32 s6, s6, 0xffffff80
	s_sub_i32 s6, s4, s6
	s_bfe_i32 s4, s6, 0x80000
	s_bfe_u32 s4, s4, 0x3000c
	s_add_i32 s10, s6, s4
	s_bfe_i32 s4, s10, 0x80000
	s_and_b32 s10, s10, 0xf8
	v_lshlrev_b32_e32 v4, 11, v4
	s_sub_i32 s6, s6, s10
	v_or_b32_e32 v5, 0xfffc0000, v4
	s_lshl_b32 s7, s7, 3
	s_sext_i32_i8 s6, s6
	v_lshlrev_b32_e32 v2, 4, v0
	v_cndmask_b32_e32 v4, v5, v4, vcc
	v_and_b32_e32 v5, 32, v0
	s_sext_i32_i16 s4, s4
	s_add_i32 s34, s7, s6
	v_bitop3_b32 v10, v2, v5, 48 bitop3:0x6c
	v_and_b32_e32 v11, 64, v0
	s_lshr_b32 s4, s4, 3
	s_lshl_b32 s10, s34, 8
	v_or_b32_e32 v2, v10, v11
	v_lshlrev_b32_e32 v3, 11, v3
	s_bfe_i64 s[6:7], s[4:5], 0x100000
	s_ashr_i32 s11, s10, 31
	s_waitcnt vmcnt(0)
	v_or_b32_e32 v130, v4, v2
	v_or_b32_e32 v4, 0xfffc0000, v3
	s_lshl_b64 s[6:7], s[6:7], 19
	s_lshl_b64 s[10:11], s[10:11], 11
	v_cndmask_b32_e32 v13, v4, v3, vcc
	v_lshrrev_b32_e32 v3, 3, v0
	s_add_u32 s30, s2, s6
	v_and_or_b32 v1, v3, 32, v1
	s_addc_u32 s31, s3, s7
	s_add_i32 s19, s12, 0
	v_lshl_or_b32 v134, v1, 11, v2
	s_add_i32 m0, s19, 0x10000
	v_and_or_b32 v1, v3, 48, v12
	global_load_lds_dwordx4 v134, s[30:31]
	s_add_i32 m0, s19, 0x12000
	s_add_u32 s6, s30, 0x40000
	global_load_lds_dwordx4 v130, s[30:31]
	s_addc_u32 s7, s31, 0
	s_add_i32 m0, s19, 0x14000
	v_lshl_or_b32 v136, v1, 11, v2
	global_load_lds_dwordx4 v134, s[6:7]
	s_add_i32 m0, s19, 0x16000
	s_add_u32 s28, s96, s10
	s_addc_u32 s29, s97, s11
	s_add_i32 s33, s19, 0x2000
	global_load_lds_dwordx4 v130, s[6:7]
	s_mov_b32 m0, s19
	s_add_u32 s6, s28, 0x40000
	v_or_b32_e32 v132, v13, v2
	global_load_lds_dwordx4 v136, s[28:29]
	s_mov_b32 m0, s33
	s_addc_u32 s7, s29, 0
	s_add_i32 s35, s19, 0x4000
	global_load_lds_dwordx4 v132, s[28:29]
	s_mov_b32 m0, s35
	s_add_i32 s38, s19, 0x6000
	global_load_lds_dwordx4 v136, s[6:7]
	s_mov_b32 m0, s38
	v_mov_b32_e32 v135, 0
	global_load_lds_dwordx4 v132, s[6:7]
	v_mov_b32_e32 v131, v135
	v_mov_b32_e32 v137, v135
	v_mov_b32_e32 v133, v135
	s_cmp_eq_u32 s9, 1
	s_mov_b32 s39, 0
	v_lshl_add_u64 v[8:9], s[30:31], 0, v[134:135]
	v_lshl_add_u64 v[6:7], s[30:31], 0, v[130:131]
	v_lshl_add_u64 v[2:3], s[28:29], 0, v[136:137]
	s_cselect_b64 s[6:7], -1, 0
	s_cmp_lg_u32 s9, 1
	v_lshl_add_u64 v[4:5], s[28:29], 0, v[132:133]
	s_cbranch_scc1 .LBB0_1613
	s_barrier

.LBB0_1722:
	s_nop 0
	s_cmp_lt_i32 s58, 19
	s_cselect_b64 s[0:1], -1, 0
	s_cmp_gt_i32 s59, 18
	s_cselect_b64 s[2:3], -1, 0
	s_and_b64 s[0:1], s[0:1], s[2:3]
	v_readlane_b32 s18, v249, 27
	s_andn2_b64 vcc, exec, s[0:1]
	v_readlane_b32 s19, v249, 28
	s_cbranch_vccnz .LBB0_1806
	s_movk_i32 s0, 0x140
	v_cmp_gt_u32_e32 vcc, s0, v0
	s_waitcnt vmcnt(0)
	s_barrier
	s_and_saveexec_b64 s[0:1], vcc
	v_add_u32_e32 v1, 0, v0
	v_mov_b32_e32 v2, 0xff
	ds_write_b8 v1, v2
	s_or_b64 exec, exec, s[0:1]
	v_readlane_b32 s0, v249, 2
	v_readlane_b32 s1, v249, 3
	s_cmpk_eq_i32 s0, 0x100
	s_cselect_b64 s[0:1], -1, 0
	v_cmp_gt_u32_e32 vcc, 64, v0
	s_and_b64 s[2:3], s[0:1], vcc
	s_waitcnt lgkmcnt(0)
	s_barrier
	s_and_saveexec_b64 s[0:1], s[2:3]
	s_cbranch_execz .LBB0_1727
	v_and_b32_e32 v1, 7, v0
	v_mul_u32_u24_e32 v1, 40, v1
	v_lshrrev_b32_e32 v2, 3, v0
	v_add3_u32 v1, v1, v2, 32
	v_lshrrev_b32_e32 v2, 2, v1
	v_and_b32_e32 v2, 0xf8, v2
	v_sub_u32_e32 v3, 0x50, v2
	v_min_u32_e32 v3, 8, v3
	v_cvt_f32_ubyte0_e32 v4, v3
	v_rcp_iflag_f32_e32 v5, v4
	v_and_b32_e32 v1, 31, v1
	v_cvt_f32_ubyte0_e32 v6, v1
	v_mul_f32_e32 v5, v6, v5
	v_trunc_f32_e32 v5, v5
	v_cvt_u32_f32_e32 v7, v5
	v_fma_f32 v5, -v5, v4, v6
	v_cmp_ge_f32_e64 vcc, |v5|, v4
	s_nop 1
	v_addc_co_u32_e32 v4, vcc, 0, v7, vcc
	v_mul_lo_u16_e32 v3, v4, v3
	v_sub_u16_e32 v1, v1, v3
	v_and_b32_e32 v1, 0xff, v1
	v_and_b32_e32 v3, 0xff, v4
	v_add_lshl_u32 v1, v2, v1, 2
	v_add3_u32 v1, 0, v1, v3
	ds_write_b8 v1, v0
